# skip dead staging work: dil staging pass exits after 4 tiles when the item only has 4 (vmcnt(0) before the barrier covers the unused in-flight loads)
# baseline (speedup 1.0000x reference)
; #define LAS __attribute__((address_space(3)))
; template <int K> __device__ __forceinline__ float swz_f(float v) { return __uint_as_float(swz_u<K>(__float_as_uint(v))); }
; #define UNPACK8(v, k) const float k##0 = blo(v.x), k##1 = bhi(v.x), k##2 = blo(v.y), k##3 = bhi(v.y), k##4 = blo(v.z), k##5 = bhi(v.z), k##6 = blo(v.w), k##7 = bhi(v.w)
; __device__ __forceinline__ unsigned cvtpk(float lo, float hi) { f32x2_t v = {lo, hi}; bf16x2_t b = __builtin_convertvector(v, bf16x2_t); return __builtin_bit_cast(unsigned, b); }
; __device__ __forceinline__ void kv_fetch(const KVSrc& s, int tid, u32x4& kc, u32x4& vc) {
;     const int kl = tid >> 3, ch = tid & 7, i = s.first + kl;
;     if (i >= s.lo && i < s.hi) { kc = *(const u32x4*)(s.k + (long)i * s.pitch + 8 * ch); vc = *(const u32x4*)(s.v + (long)i * s.pitch + 8 * ch); }
;     else { kc = (u32x4){0u, 0u, 0u, 0u}; vc = kc; }
; }
; template <bool NORM> __device__ __forceinline__ void kv_store(u32x4 kc, u32x4 vc, const float (&g)[8], LAS unsigned char* ksb, LAS unsigned char* vtb, int tid) {
;     const int kl = tid >> 3, ch = tid & 7;
;     if (NORM) { UNPACK8(kc, k); float ss = (k0 * k0 + k1 * k1) + (k2 * k2 + k3 * k3) + (k4 * k4 + k5 * k5) + (k6 * k6 + k7 * k7);
;         ss += swz_f<1>(ss); ss += swz_f<2>(ss); ss += swz_f<4>(ss);
;         const float rs = rsqrtf(ss * (1.f / 64.f) + EPS);
;         kc.x = cvtpk(k0 * rs * g[0], k1 * rs * g[1]); kc.y = cvtpk(k2 * rs * g[2], k3 * rs * g[3]); kc.z = cvtpk(k4 * rs * g[4], k5 * rs * g[5]); kc.w = cvtpk(k6 * rs * g[6], k7 * rs * g[7]); }
;     *(LAS u32x4*)(ksb + kl * KSB + ch * 16) = kc;
;     LAS unsigned short* vp = (LAS unsigned short*)(vtb + (8 * ch) * VTB + kl * 2);
;     vp[0 * (VTB / 2)] = (unsigned short)(vc.x & 0xffffu); vp[1 * (VTB / 2)] = (unsigned short)(vc.x >> 16);
;     vp[2 * (VTB / 2)] = (unsigned short)(vc.y & 0xffffu); vp[3 * (VTB / 2)] = (unsigned short)(vc.y >> 16);
;     vp[4 * (VTB / 2)] = (unsigned short)(vc.z & 0xffffu); vp[5 * (VTB / 2)] = (unsigned short)(vc.z >> 16);
;     vp[6 * (VTB / 2)] = (unsigned short)(vc.w & 0xffffu); vp[7 * (VTB / 2)] = (unsigned short)(vc.w >> 16);
.LBB0_863:
	s_add_i32 s101, s30, -1
	s_add_i32 s0, s43, 0
	v_add_u32_e32 v185, s0, v114
	v_min_i32_e32 v185, s101, v185
	v_mad_u64_u32 v[64:65], s[26:27], s44, v185, 0
	v_lshlrev_b64 v[64:65], 1, v[64:65]
	v_lshl_add_u64 v[66:67], v[102:103], 0, v[64:65]
	v_lshl_add_u64 v[68:69], v[104:105], 0, v[64:65]
	global_load_dwordx4 v[64:67], v[66:67], off
	s_nop 0
	global_load_dwordx4 v[68:71], v[68:69], off
	s_add_i32 s0, s43, 64
	v_add_u32_e32 v185, s0, v114
	v_min_i32_e32 v185, s101, v185
	v_mad_u64_u32 v[72:73], s[26:27], s44, v185, 0
	v_lshlrev_b64 v[72:73], 1, v[72:73]
	v_lshl_add_u64 v[74:75], v[102:103], 0, v[72:73]
	v_lshl_add_u64 v[76:77], v[104:105], 0, v[72:73]
	global_load_dwordx4 v[72:75], v[74:75], off
	s_nop 0
	global_load_dwordx4 v[76:79], v[76:77], off
	s_add_i32 s0, s43, 128
	v_add_u32_e32 v185, s0, v114
	v_min_i32_e32 v185, s101, v185
	v_mad_u64_u32 v[190:191], s[26:27], s44, v185, 0
	v_lshlrev_b64 v[190:191], 1, v[190:191]
	v_lshl_add_u64 v[192:193], v[102:103], 0, v[190:191]
	v_lshl_add_u64 v[194:195], v[104:105], 0, v[190:191]
	global_load_dwordx4 v[190:193], v[192:193], off
	s_nop 0
	global_load_dwordx4 v[194:197], v[194:195], off
	s_add_i32 s0, s43, 192
	v_add_u32_e32 v185, s0, v114
	v_min_i32_e32 v185, s101, v185
	v_mad_u64_u32 v[198:199], s[26:27], s44, v185, 0
	v_lshlrev_b64 v[198:199], 1, v[198:199]
	v_lshl_add_u64 v[200:201], v[102:103], 0, v[198:199]
	v_lshl_add_u64 v[202:203], v[104:105], 0, v[198:199]
	global_load_dwordx4 v[198:201], v[200:201], off
	s_nop 0
	global_load_dwordx4 v[202:205], v[202:203], off
	s_add_i32 s0, s43, 256
	v_add_u32_e32 v185, s0, v114
	v_min_i32_e32 v185, s101, v185
	v_mad_u64_u32 v[116:117], s[26:27], s44, v185, 0
	v_lshlrev_b64 v[116:117], 1, v[116:117]
	v_lshl_add_u64 v[118:119], v[102:103], 0, v[116:117]
	v_lshl_add_u64 v[120:121], v[104:105], 0, v[116:117]
	global_load_dwordx4 v[116:119], v[118:119], off
	s_nop 0
	global_load_dwordx4 v[120:123], v[120:121], off
	s_waitcnt vmcnt(11)
	v_and_b32_e32 v53, 0xffff0000, v5
	v_and_b32_e32 v51, 0xffff0000, v4
	v_lshlrev_b32_e32 v52, 16, v5
	v_lshlrev_b32_e32 v50, 16, v4
	v_pk_mul_f32 v[48:49], v[50:51], v[50:51]
	v_and_b32_e32 v57, 0xffff0000, v2
	v_and_b32_e32 v55, 0xffff0000, v3
	v_lshlrev_b32_e32 v54, 16, v3
	v_lshlrev_b32_e32 v56, 16, v2
	v_pk_fma_f32 v[48:49], v[52:53], v[52:53], v[48:49]
	s_mul_i32 s0, s6, 0x2400
	s_mul_i32 s98, s6, 0x3000
	s_add_i32 s98, s98, 0x9000
	s_add_i32 s16, s0, 0
	v_pk_fma_f32 v[48:49], v[54:55], v[54:55], v[48:49]
	v_pk_fma_f32 v[48:49], v[56:57], v[56:57], v[48:49]
	v_add_f32_e32 v48, v48, v49
	s_lshl_b32 s0, s6, 9
	s_sub_i32 s9, s16, s0
	s_cmp_ge_u32 s13, s24
	s_cselect_b64 s[4:5], -1, 0
	s_nop 1
	v_add_f32_dpp v48, v48, v48 quad_perm:[1,0,3,2] row_mask:0xf bank_mask:0xf
	s_nop 1
	v_add_f32_dpp v48, v48, v48 quad_perm:[2,3,0,1] row_mask:0xf bank_mask:0xf
	s_nop 1
	v_add_f32_dpp v48, v48, v48 row_half_mirror row_mask:0xf bank_mask:0xf
	v_fmamk_f32 v48, v48, 0x3c800000, v139
	v_rsq_f32_e32 v58, v48
	s_nop 0
	v_pk_mul_f32 v[48:49], v[58:59], v[56:57] op_sel_hi:[0,1]
	v_pk_mul_f32 v[54:55], v[58:59], v[54:55] op_sel_hi:[0,1]
	v_pk_mul_f32 v[50:51], v[58:59], v[50:51] op_sel_hi:[0,1]
	v_pk_mul_f32 v[52:53], v[58:59], v[52:53] op_sel_hi:[0,1]
	v_pk_mul_f32 v[48:49], v[14:15], v[48:49]
	v_pk_mul_f32 v[54:55], v[96:97], v[54:55]
	v_pk_mul_f32 v[50:51], v[98:99], v[50:51]
	v_pk_mul_f32 v[52:53], v[100:101], v[52:53]
	v_cvt_pk_bf16_f32 v48, v48, v49
	v_cvt_pk_bf16_f32 v49, v54, v55
	v_cvt_pk_bf16_f32 v50, v50, v51
	v_cvt_pk_bf16_f32 v51, v52, v53
	v_add3_u32 v52, s16, v95, v108
	ds_write_b128 v52, v[48:51]
	v_add_u32_e32 v48, s98, v110
	s_and_b64 vcc, exec, s[4:5]
	s_waitcnt vmcnt(10)
	ds_write_b128 v48, v[6:9] offset:18432
	s_add_i32 s6, s6, 1
	s_waitcnt vmcnt(9)
	v_and_b32_e32 v53, 0xffff0000, v67
	v_and_b32_e32 v51, 0xffff0000, v66
	v_lshlrev_b32_e32 v52, 16, v67
	v_lshlrev_b32_e32 v50, 16, v66
	v_pk_mul_f32 v[48:49], v[50:51], v[50:51]
	v_and_b32_e32 v57, 0xffff0000, v64
	v_and_b32_e32 v55, 0xffff0000, v65
	v_lshlrev_b32_e32 v54, 16, v65
	v_lshlrev_b32_e32 v56, 16, v64
	v_pk_fma_f32 v[48:49], v[52:53], v[52:53], v[48:49]
	s_mul_i32 s0, s6, 0x2400
	s_mul_i32 s98, s6, 0x3000
	s_add_i32 s98, s98, 0x9000
	s_add_i32 s16, s0, 0
	v_pk_fma_f32 v[48:49], v[54:55], v[54:55], v[48:49]
	v_pk_fma_f32 v[48:49], v[56:57], v[56:57], v[48:49]
	v_add_f32_e32 v48, v48, v49
	s_lshl_b32 s0, s6, 9
	s_sub_i32 s9, s16, s0
	s_cmp_ge_u32 s13, s24
	s_cselect_b64 s[4:5], -1, 0
	s_nop 1
	v_add_f32_dpp v48, v48, v48 quad_perm:[1,0,3,2] row_mask:0xf bank_mask:0xf
	s_nop 1
	v_add_f32_dpp v48, v48, v48 quad_perm:[2,3,0,1] row_mask:0xf bank_mask:0xf
	s_nop 1
	v_add_f32_dpp v48, v48, v48 row_half_mirror row_mask:0xf bank_mask:0xf
	v_fmamk_f32 v48, v48, 0x3c800000, v139
	v_rsq_f32_e32 v58, v48
	s_nop 0
	v_pk_mul_f32 v[48:49], v[58:59], v[56:57] op_sel_hi:[0,1]
	v_pk_mul_f32 v[54:55], v[58:59], v[54:55] op_sel_hi:[0,1]
	v_pk_mul_f32 v[50:51], v[58:59], v[50:51] op_sel_hi:[0,1]
	v_pk_mul_f32 v[52:53], v[58:59], v[52:53] op_sel_hi:[0,1]
	v_pk_mul_f32 v[48:49], v[14:15], v[48:49]
	v_pk_mul_f32 v[54:55], v[96:97], v[54:55]
	v_pk_mul_f32 v[50:51], v[98:99], v[50:51]
	v_pk_mul_f32 v[52:53], v[100:101], v[52:53]
	v_cvt_pk_bf16_f32 v48, v48, v49
	v_cvt_pk_bf16_f32 v49, v54, v55
	v_cvt_pk_bf16_f32 v50, v50, v51
	v_cvt_pk_bf16_f32 v51, v52, v53
	v_add3_u32 v52, s16, v95, v108
	ds_write_b128 v52, v[48:51]
	v_add_u32_e32 v48, s98, v110
	s_and_b64 vcc, exec, s[4:5]
	s_waitcnt vmcnt(8)
	ds_write_b128 v48, v[68:71] offset:18432
	s_add_i32 s6, s6, 1
	s_waitcnt vmcnt(7)
; #define LAS __attribute__((address_space(3)))
; template <int K> __device__ __forceinline__ float swz_f(float v) { return __uint_as_float(swz_u<K>(__float_as_uint(v))); }
; #define UNPACK8(v, k) const float k##0 = blo(v.x), k##1 = bhi(v.x), k##2 = blo(v.y), k##3 = bhi(v.y), k##4 = blo(v.z), k##5 = bhi(v.z), k##6 = blo(v.w), k##7 = bhi(v.w)
; __device__ __forceinline__ unsigned cvtpk(float lo, float hi) { f32x2_t v = {lo, hi}; bf16x2_t b = __builtin_convertvector(v, bf16x2_t); return __builtin_bit_cast(unsigned, b); }
; template <bool NORM> __device__ __forceinline__ void kv_store(u32x4 kc, u32x4 vc, const float (&g)[8], LAS unsigned char* ksb, LAS unsigned char* vtb, int tid) {
;     const int kl = tid >> 3, ch = tid & 7;
;     if (NORM) { UNPACK8(kc, k); float ss = (k0 * k0 + k1 * k1) + (k2 * k2 + k3 * k3) + (k4 * k4 + k5 * k5) + (k6 * k6 + k7 * k7);
;         ss += swz_f<1>(ss); ss += swz_f<2>(ss); ss += swz_f<4>(ss);
;         const float rs = rsqrtf(ss * (1.f / 64.f) + EPS);
;         kc.x = cvtpk(k0 * rs * g[0], k1 * rs * g[1]); kc.y = cvtpk(k2 * rs * g[2], k3 * rs * g[3]); kc.z = cvtpk(k4 * rs * g[4], k5 * rs * g[5]); kc.w = cvtpk(k6 * rs * g[6], k7 * rs * g[7]); }
;     *(LAS u32x4*)(ksb + kl * KSB + ch * 16) = kc;
;     LAS unsigned short* vp = (LAS unsigned short*)(vtb + (8 * ch) * VTB + kl * 2);
;     vp[0 * (VTB / 2)] = (unsigned short)(vc.x & 0xffffu); vp[1 * (VTB / 2)] = (unsigned short)(vc.x >> 16);
;     vp[2 * (VTB / 2)] = (unsigned short)(vc.y & 0xffffu); vp[3 * (VTB / 2)] = (unsigned short)(vc.y >> 16);
;     vp[4 * (VTB / 2)] = (unsigned short)(vc.z & 0xffffu); vp[5 * (VTB / 2)] = (unsigned short)(vc.z >> 16);
;     vp[6 * (VTB / 2)] = (unsigned short)(vc.w & 0xffffu); vp[7 * (VTB / 2)] = (unsigned short)(vc.w >> 16);
	v_and_b32_e32 v53, 0xffff0000, v75
	v_and_b32_e32 v51, 0xffff0000, v74
	v_lshlrev_b32_e32 v52, 16, v75
	v_lshlrev_b32_e32 v50, 16, v74
	v_pk_mul_f32 v[48:49], v[50:51], v[50:51]
	v_and_b32_e32 v57, 0xffff0000, v72
	v_and_b32_e32 v55, 0xffff0000, v73
	v_lshlrev_b32_e32 v54, 16, v73
	v_lshlrev_b32_e32 v56, 16, v72
	v_pk_fma_f32 v[48:49], v[52:53], v[52:53], v[48:49]
	s_mul_i32 s0, s6, 0x2400
	s_mul_i32 s98, s6, 0x3000
	s_add_i32 s98, s98, 0x9000
	s_add_i32 s16, s0, 0
	v_pk_fma_f32 v[48:49], v[54:55], v[54:55], v[48:49]
	v_pk_fma_f32 v[48:49], v[56:57], v[56:57], v[48:49]
	v_add_f32_e32 v48, v48, v49
	s_lshl_b32 s0, s6, 9
	s_sub_i32 s9, s16, s0
	s_cmp_ge_u32 s13, s24
	s_cselect_b64 s[4:5], -1, 0
	s_nop 1
	v_add_f32_dpp v48, v48, v48 quad_perm:[1,0,3,2] row_mask:0xf bank_mask:0xf
	s_nop 1
	v_add_f32_dpp v48, v48, v48 quad_perm:[2,3,0,1] row_mask:0xf bank_mask:0xf
	s_nop 1
	v_add_f32_dpp v48, v48, v48 row_half_mirror row_mask:0xf bank_mask:0xf
	v_fmamk_f32 v48, v48, 0x3c800000, v139
	v_rsq_f32_e32 v58, v48
	s_nop 0
	v_pk_mul_f32 v[48:49], v[58:59], v[56:57] op_sel_hi:[0,1]
	v_pk_mul_f32 v[54:55], v[58:59], v[54:55] op_sel_hi:[0,1]
	v_pk_mul_f32 v[50:51], v[58:59], v[50:51] op_sel_hi:[0,1]
	v_pk_mul_f32 v[52:53], v[58:59], v[52:53] op_sel_hi:[0,1]
	v_pk_mul_f32 v[48:49], v[14:15], v[48:49]
	v_pk_mul_f32 v[54:55], v[96:97], v[54:55]
	v_pk_mul_f32 v[50:51], v[98:99], v[50:51]
	v_pk_mul_f32 v[52:53], v[100:101], v[52:53]
	v_cvt_pk_bf16_f32 v48, v48, v49
	v_cvt_pk_bf16_f32 v49, v54, v55
	v_cvt_pk_bf16_f32 v50, v50, v51
	v_cvt_pk_bf16_f32 v51, v52, v53
	v_add3_u32 v52, s16, v95, v108
	ds_write_b128 v52, v[48:51]
	v_add_u32_e32 v48, s98, v110
	s_and_b64 vcc, exec, s[4:5]
	s_waitcnt vmcnt(6)
	ds_write_b128 v48, v[76:79] offset:18432
	s_add_i32 s6, s6, 1
	s_waitcnt vmcnt(5)
	v_and_b32_e32 v53, 0xffff0000, v193
	v_and_b32_e32 v51, 0xffff0000, v192
	v_lshlrev_b32_e32 v52, 16, v193
	v_lshlrev_b32_e32 v50, 16, v192
	v_pk_mul_f32 v[48:49], v[50:51], v[50:51]
	v_and_b32_e32 v57, 0xffff0000, v190
	v_and_b32_e32 v55, 0xffff0000, v191
	v_lshlrev_b32_e32 v54, 16, v191
	v_lshlrev_b32_e32 v56, 16, v190
	v_pk_fma_f32 v[48:49], v[52:53], v[52:53], v[48:49]
	s_mul_i32 s0, s6, 0x2400
	s_mul_i32 s98, s6, 0x3000
	s_add_i32 s98, s98, 0x9000
	s_add_i32 s16, s0, 0
	v_pk_fma_f32 v[48:49], v[54:55], v[54:55], v[48:49]
	v_pk_fma_f32 v[48:49], v[56:57], v[56:57], v[48:49]
	v_add_f32_e32 v48, v48, v49
	s_lshl_b32 s0, s6, 9
	s_sub_i32 s9, s16, s0
	s_cmp_ge_u32 s13, s24
	s_cselect_b64 s[4:5], -1, 0
	s_nop 1
	v_add_f32_dpp v48, v48, v48 quad_perm:[1,0,3,2] row_mask:0xf bank_mask:0xf
	s_nop 1
	v_add_f32_dpp v48, v48, v48 quad_perm:[2,3,0,1] row_mask:0xf bank_mask:0xf
	s_nop 1
	v_add_f32_dpp v48, v48, v48 row_half_mirror row_mask:0xf bank_mask:0xf
	v_fmamk_f32 v48, v48, 0x3c800000, v139
	v_rsq_f32_e32 v58, v48
	s_nop 0
	v_pk_mul_f32 v[48:49], v[58:59], v[56:57] op_sel_hi:[0,1]
	v_pk_mul_f32 v[54:55], v[58:59], v[54:55] op_sel_hi:[0,1]
	v_pk_mul_f32 v[50:51], v[58:59], v[50:51] op_sel_hi:[0,1]
	v_pk_mul_f32 v[52:53], v[58:59], v[52:53] op_sel_hi:[0,1]
	v_pk_mul_f32 v[48:49], v[14:15], v[48:49]
	v_pk_mul_f32 v[54:55], v[96:97], v[54:55]
	v_pk_mul_f32 v[50:51], v[98:99], v[50:51]
	v_pk_mul_f32 v[52:53], v[100:101], v[52:53]
	v_cvt_pk_bf16_f32 v48, v48, v49
	v_cvt_pk_bf16_f32 v49, v54, v55
	v_cvt_pk_bf16_f32 v50, v50, v51
	v_cvt_pk_bf16_f32 v51, v52, v53
	v_add3_u32 v52, s16, v95, v108
	ds_write_b128 v52, v[48:51]
	v_add_u32_e32 v48, s98, v110
	s_and_b64 vcc, exec, s[4:5]
	s_waitcnt vmcnt(4)
	ds_write_b128 v48, v[194:197] offset:18432
	s_add_i32 s6, s6, 1
	s_add_i32 s0, s13, 4
	s_cmp_gt_u32 s0, s24
	s_cbranch_scc1 .LdilA_done
; #define LAS __attribute__((address_space(3)))
; template <int K> __device__ __forceinline__ float swz_f(float v) { return __uint_as_float(swz_u<K>(__float_as_uint(v))); }
; #define UNPACK8(v, k) const float k##0 = blo(v.x), k##1 = bhi(v.x), k##2 = blo(v.y), k##3 = bhi(v.y), k##4 = blo(v.z), k##5 = bhi(v.z), k##6 = blo(v.w), k##7 = bhi(v.w)
; __device__ __forceinline__ unsigned cvtpk(float lo, float hi) { f32x2_t v = {lo, hi}; bf16x2_t b = __builtin_convertvector(v, bf16x2_t); return __builtin_bit_cast(unsigned, b); }
; template <bool NORM> __device__ __forceinline__ void kv_store(u32x4 kc, u32x4 vc, const float (&g)[8], LAS unsigned char* ksb, LAS unsigned char* vtb, int tid) {
;     const int kl = tid >> 3, ch = tid & 7;
;     if (NORM) { UNPACK8(kc, k); float ss = (k0 * k0 + k1 * k1) + (k2 * k2 + k3 * k3) + (k4 * k4 + k5 * k5) + (k6 * k6 + k7 * k7);
;         ss += swz_f<1>(ss); ss += swz_f<2>(ss); ss += swz_f<4>(ss);
;         const float rs = rsqrtf(ss * (1.f / 64.f) + EPS);
;         kc.x = cvtpk(k0 * rs * g[0], k1 * rs * g[1]); kc.y = cvtpk(k2 * rs * g[2], k3 * rs * g[3]); kc.z = cvtpk(k4 * rs * g[4], k5 * rs * g[5]); kc.w = cvtpk(k6 * rs * g[6], k7 * rs * g[7]); }
;     *(LAS u32x4*)(ksb + kl * KSB + ch * 16) = kc;
;     LAS unsigned short* vp = (LAS unsigned short*)(vtb + (8 * ch) * VTB + kl * 2);
;     vp[0 * (VTB / 2)] = (unsigned short)(vc.x & 0xffffu); vp[1 * (VTB / 2)] = (unsigned short)(vc.x >> 16);
;     vp[2 * (VTB / 2)] = (unsigned short)(vc.y & 0xffffu); vp[3 * (VTB / 2)] = (unsigned short)(vc.y >> 16);
;     vp[4 * (VTB / 2)] = (unsigned short)(vc.z & 0xffffu); vp[5 * (VTB / 2)] = (unsigned short)(vc.z >> 16);
;     vp[6 * (VTB / 2)] = (unsigned short)(vc.w & 0xffffu); vp[7 * (VTB / 2)] = (unsigned short)(vc.w >> 16);
	s_waitcnt vmcnt(3)
	v_and_b32_e32 v53, 0xffff0000, v201
	v_and_b32_e32 v51, 0xffff0000, v200
	v_lshlrev_b32_e32 v52, 16, v201
	v_lshlrev_b32_e32 v50, 16, v200
	v_pk_mul_f32 v[48:49], v[50:51], v[50:51]
	v_and_b32_e32 v57, 0xffff0000, v198
	v_and_b32_e32 v55, 0xffff0000, v199
	v_lshlrev_b32_e32 v54, 16, v199
	v_lshlrev_b32_e32 v56, 16, v198
	v_pk_fma_f32 v[48:49], v[52:53], v[52:53], v[48:49]
	s_mul_i32 s0, s6, 0x2400
	s_mul_i32 s98, s6, 0x3000
	s_add_i32 s98, s98, 0x9000
	s_add_i32 s16, s0, 0
	v_pk_fma_f32 v[48:49], v[54:55], v[54:55], v[48:49]
	v_pk_fma_f32 v[48:49], v[56:57], v[56:57], v[48:49]
	v_add_f32_e32 v48, v48, v49
	s_lshl_b32 s0, s6, 9
	s_sub_i32 s9, s16, s0
	s_cmp_ge_u32 s13, s24
	s_cselect_b64 s[4:5], -1, 0
	s_nop 1
	v_add_f32_dpp v48, v48, v48 quad_perm:[1,0,3,2] row_mask:0xf bank_mask:0xf
	s_nop 1
	v_add_f32_dpp v48, v48, v48 quad_perm:[2,3,0,1] row_mask:0xf bank_mask:0xf
	s_nop 1
	v_add_f32_dpp v48, v48, v48 row_half_mirror row_mask:0xf bank_mask:0xf
	v_fmamk_f32 v48, v48, 0x3c800000, v139
	v_rsq_f32_e32 v58, v48
	s_nop 0
	v_pk_mul_f32 v[48:49], v[58:59], v[56:57] op_sel_hi:[0,1]
	v_pk_mul_f32 v[54:55], v[58:59], v[54:55] op_sel_hi:[0,1]
	v_pk_mul_f32 v[50:51], v[58:59], v[50:51] op_sel_hi:[0,1]
	v_pk_mul_f32 v[52:53], v[58:59], v[52:53] op_sel_hi:[0,1]
	v_pk_mul_f32 v[48:49], v[14:15], v[48:49]
	v_pk_mul_f32 v[54:55], v[96:97], v[54:55]
	v_pk_mul_f32 v[50:51], v[98:99], v[50:51]
	v_pk_mul_f32 v[52:53], v[100:101], v[52:53]
	v_cvt_pk_bf16_f32 v48, v48, v49
	v_cvt_pk_bf16_f32 v49, v54, v55
	v_cvt_pk_bf16_f32 v50, v50, v51
	v_cvt_pk_bf16_f32 v51, v52, v53
	v_add3_u32 v52, s16, v95, v108
	ds_write_b128 v52, v[48:51]
	v_add_u32_e32 v48, s98, v110
	s_and_b64 vcc, exec, s[4:5]
	s_waitcnt vmcnt(2)
	ds_write_b128 v48, v[202:205] offset:18432
	s_add_i32 s6, s6, 1
	s_waitcnt vmcnt(1)
	v_and_b32_e32 v53, 0xffff0000, v119
	v_and_b32_e32 v51, 0xffff0000, v118
	v_lshlrev_b32_e32 v52, 16, v119
	v_lshlrev_b32_e32 v50, 16, v118
	v_pk_mul_f32 v[48:49], v[50:51], v[50:51]
	v_and_b32_e32 v57, 0xffff0000, v116
	v_and_b32_e32 v55, 0xffff0000, v117
	v_lshlrev_b32_e32 v54, 16, v117
	v_lshlrev_b32_e32 v56, 16, v116
	v_pk_fma_f32 v[48:49], v[52:53], v[52:53], v[48:49]
	s_mul_i32 s0, s6, 0x2400
	s_mul_i32 s98, s6, 0x3000
	s_add_i32 s98, s98, 0x9000
	s_add_i32 s16, s0, 0
	v_pk_fma_f32 v[48:49], v[54:55], v[54:55], v[48:49]
	v_pk_fma_f32 v[48:49], v[56:57], v[56:57], v[48:49]
	v_add_f32_e32 v48, v48, v49
	s_lshl_b32 s0, s6, 9
	s_sub_i32 s9, s16, s0
	s_cmp_ge_u32 s13, s24
	s_cselect_b64 s[4:5], -1, 0
	s_nop 1
	v_add_f32_dpp v48, v48, v48 quad_perm:[1,0,3,2] row_mask:0xf bank_mask:0xf
	s_nop 1
	v_add_f32_dpp v48, v48, v48 quad_perm:[2,3,0,1] row_mask:0xf bank_mask:0xf
	s_nop 1
	v_add_f32_dpp v48, v48, v48 row_half_mirror row_mask:0xf bank_mask:0xf
	v_fmamk_f32 v48, v48, 0x3c800000, v139
	v_rsq_f32_e32 v58, v48
	s_nop 0
	v_pk_mul_f32 v[48:49], v[58:59], v[56:57] op_sel_hi:[0,1]
	v_pk_mul_f32 v[54:55], v[58:59], v[54:55] op_sel_hi:[0,1]
	v_pk_mul_f32 v[50:51], v[58:59], v[50:51] op_sel_hi:[0,1]
	v_pk_mul_f32 v[52:53], v[58:59], v[52:53] op_sel_hi:[0,1]
	v_pk_mul_f32 v[48:49], v[14:15], v[48:49]
	v_pk_mul_f32 v[54:55], v[96:97], v[54:55]
	v_pk_mul_f32 v[50:51], v[98:99], v[50:51]
	v_pk_mul_f32 v[52:53], v[100:101], v[52:53]
	v_cvt_pk_bf16_f32 v48, v48, v49
	v_cvt_pk_bf16_f32 v49, v54, v55
	v_cvt_pk_bf16_f32 v50, v50, v51
	v_cvt_pk_bf16_f32 v51, v52, v53
	v_add3_u32 v52, s16, v95, v108
	ds_write_b128 v52, v[48:51]
	v_add_u32_e32 v48, s98, v110
	s_and_b64 vcc, exec, s[4:5]
	s_waitcnt vmcnt(0)
	ds_write_b128 v48, v[120:123] offset:18432
.LdilA_done:
	s_waitcnt vmcnt(0)
	s_waitcnt lgkmcnt(0)
	s_barrier
	s_mov_b32 s13, s99
	s_lshl_b32 s43, s13, 6
	s_mov_b32 s6, 0
